# code placement: in-proj k-loop (and everything after it) shifted by 4 bytes so three of its four MFMA clusters start at 0 mod 8
# speedup vs baseline: 1.0142x; 1.0003x over previous
.LBB0_580:
	s_nop 0
	s_ashr_i32 s49, s48, 31
	s_lshl_b64 s[8:9], s[48:49], 19
	s_add_u32 s50, s30, s8
	s_addc_u32 s51, s31, s9
	s_and_b64 s[8:9], s[38:39], exec
	s_cselect_b32 s8, s51, s1
	s_cselect_b32 s9, s50, s0
	s_ashr_i32 s47, s46, 31
	s_lshl_b64 s[18:19], s[46:47], 19
	s_add_u32 s52, s90, s18
	s_addc_u32 s53, s91, s19
	s_and_b64 s[18:19], s[38:39], exec
	s_cselect_b32 s10, s53, s5
	s_cselect_b32 s18, s52, s4
	s_add_u32 s0, s0, 0x40080
	s_addc_u32 s1, s1, 0
	s_add_u32 s19, s4, 0x100
	v_mov_b32_e32 v0, 0
	s_addc_u32 s20, s5, 0
	s_mov_b32 s21, -2
	v_mov_b32_e32 v1, v0
	v_mov_b32_e32 v2, v0
	v_mov_b32_e32 v3, v0
	v_mov_b32_e32 v4, v0
	v_mov_b32_e32 v5, v0
	v_mov_b32_e32 v6, v0
	v_mov_b32_e32 v7, v0
	v_mov_b32_e32 v16, v0
	v_mov_b32_e32 v17, v0
	v_mov_b32_e32 v18, v0
	v_mov_b32_e32 v19, v0
	v_mov_b32_e32 v20, v0
	v_mov_b32_e32 v21, v0
	v_mov_b32_e32 v22, v0
	v_mov_b32_e32 v23, v0
	v_mov_b32_e32 v32, v0
	v_mov_b32_e32 v33, v0
	v_mov_b32_e32 v34, v0
	v_mov_b32_e32 v35, v0
	v_mov_b32_e32 v36, v0
	v_mov_b32_e32 v37, v0
	v_mov_b32_e32 v38, v0
	v_mov_b32_e32 v39, v0
	v_mov_b32_e32 v48, v0
	v_mov_b32_e32 v49, v0
	v_mov_b32_e32 v50, v0
	v_mov_b32_e32 v51, v0
	v_mov_b32_e32 v52, v0
	v_mov_b32_e32 v53, v0
	v_mov_b32_e32 v54, v0
	v_mov_b32_e32 v55, v0
	v_mov_b32_e32 v8, v0
	v_mov_b32_e32 v9, v0
	v_mov_b32_e32 v10, v0
	v_mov_b32_e32 v11, v0
	v_mov_b32_e32 v12, v0
	v_mov_b32_e32 v13, v0
	v_mov_b32_e32 v14, v0
	v_mov_b32_e32 v15, v0
	v_mov_b32_e32 v24, v0
	v_mov_b32_e32 v25, v0
	v_mov_b32_e32 v26, v0
	v_mov_b32_e32 v27, v0
	v_mov_b32_e32 v28, v0
	v_mov_b32_e32 v29, v0
	v_mov_b32_e32 v30, v0
	v_mov_b32_e32 v31, v0
	v_mov_b32_e32 v40, v0
	v_mov_b32_e32 v41, v0
	v_mov_b32_e32 v42, v0
	v_mov_b32_e32 v43, v0
	v_mov_b32_e32 v44, v0
	v_mov_b32_e32 v45, v0
	v_mov_b32_e32 v46, v0
	v_mov_b32_e32 v47, v0
	v_mov_b32_e32 v56, v0
	v_mov_b32_e32 v57, v0
	v_mov_b32_e32 v58, v0
	v_mov_b32_e32 v59, v0
	v_mov_b32_e32 v60, v0
	v_mov_b32_e32 v61, v0
	v_mov_b32_e32 v62, v0
	v_mov_b32_e32 v63, v0
	v_mov_b32_e32 v66, v0
	v_mov_b32_e32 v67, v0
	v_mov_b32_e32 v68, v0
	v_mov_b32_e32 v69, v0
	v_mov_b32_e32 v70, v0
	v_mov_b32_e32 v71, v0
	v_mov_b32_e32 v72, v0
	v_mov_b32_e32 v73, v0
	v_mov_b32_e32 v82, v0
	v_mov_b32_e32 v83, v0
	v_mov_b32_e32 v84, v0
	v_mov_b32_e32 v85, v0
	v_mov_b32_e32 v86, v0
	v_mov_b32_e32 v87, v0
	v_mov_b32_e32 v88, v0
	v_mov_b32_e32 v89, v0
	v_mov_b32_e32 v98, v0
	v_mov_b32_e32 v99, v0
	v_mov_b32_e32 v100, v0
	v_mov_b32_e32 v101, v0
	v_mov_b32_e32 v102, v0
	v_mov_b32_e32 v103, v0
	v_mov_b32_e32 v104, v0
	v_mov_b32_e32 v105, v0
	v_mov_b32_e32 v114, v0
	v_mov_b32_e32 v115, v0
	v_mov_b32_e32 v116, v0
	v_mov_b32_e32 v117, v0
	v_mov_b32_e32 v118, v0
	v_mov_b32_e32 v119, v0
	v_mov_b32_e32 v120, v0
	v_mov_b32_e32 v121, v0
	v_mov_b32_e32 v74, v0
	v_mov_b32_e32 v75, v0
	v_mov_b32_e32 v76, v0
	v_mov_b32_e32 v77, v0
	v_mov_b32_e32 v78, v0
	v_mov_b32_e32 v79, v0
	v_mov_b32_e32 v80, v0
	v_mov_b32_e32 v81, v0
	v_mov_b32_e32 v90, v0
	v_mov_b32_e32 v91, v0
	v_mov_b32_e32 v92, v0
	v_mov_b32_e32 v93, v0
	v_mov_b32_e32 v94, v0
	v_mov_b32_e32 v95, v0
	v_mov_b32_e32 v96, v0
	v_mov_b32_e32 v97, v0
	v_mov_b32_e32 v106, v0
	v_mov_b32_e32 v107, v0
	v_mov_b32_e32 v108, v0
	v_mov_b32_e32 v109, v0
	v_mov_b32_e32 v110, v0
	v_mov_b32_e32 v111, v0
	v_mov_b32_e32 v112, v0
	v_mov_b32_e32 v113, v0
	v_mov_b32_e32 v122, v0
	v_mov_b32_e32 v123, v0
	v_mov_b32_e32 v124, v0
	v_mov_b32_e32 v125, v0
	v_mov_b32_e32 v126, v0
	v_mov_b32_e32 v127, v0
	v_mov_b32_e32 v128, v0
	v_mov_b32_e32 v129, v0
